# plus layer-0 attention tile loops rescale the O accumulators in place (16 packed multiplies read/write the same registers) so the 32 loop-carried register copies per tile disappear
# baseline (speedup 1.0000x reference)
.LBB0_1145:
	s_waitcnt lgkmcnt(0)
	v_add_f32_e32 v65, v65, v230
	v_cmp_gt_u32_e32 vcc, s46, v187
	v_add_f32_e32 v48, v48, v229
	v_add_f32_e32 v47, v47, v225
	v_cndmask_b32_e32 v187, v137, v65, vcc
	v_cmp_gt_u32_e32 vcc, s46, v228
	v_add_f32_e32 v46, v46, v221
	v_add_f32_e32 v45, v45, v217
	v_cndmask_b32_e32 v228, v137, v48, vcc
	v_add_f32_e32 v48, v64, v227
	v_cmp_gt_u32_e32 vcc, s46, v226
	v_add_f32_e32 v44, v44, v213
	v_add_f32_e32 v43, v43, v209
	v_cndmask_b32_e32 v226, v137, v48, vcc
	v_cmp_gt_u32_e32 vcc, s46, v224
	v_add_f32_e32 v42, v42, v205
	v_add_f32_e32 v41, v41, v201
	v_cndmask_b32_e32 v224, v137, v47, vcc
	v_add_f32_e32 v47, v63, v223
	v_cmp_gt_u32_e32 vcc, s46, v222
	v_add_f32_e32 v40, v40, v197
	v_add_f32_e32 v39, v39, v193
	v_cndmask_b32_e32 v64, v137, v47, vcc
	v_cmp_gt_u32_e32 vcc, s46, v220
	v_add_f32_e32 v38, v38, v189
	v_add_f32_e32 v37, v37, v183
	v_cndmask_b32_e32 v220, v137, v46, vcc
	v_add_f32_e32 v46, v62, v219
	v_cmp_gt_u32_e32 vcc, s46, v218
	v_add_f32_e32 v36, v36, v179
	v_add_f32_e32 v35, v35, v175
	v_cndmask_b32_e32 v62, v137, v46, vcc
	v_cmp_gt_u32_e32 vcc, s46, v216
	v_add_f32_e32 v34, v34, v171
	v_add_f32_e32 v0, v49, v0
	v_cndmask_b32_e32 v48, v137, v45, vcc
	v_add_f32_e32 v45, v61, v215
	v_cmp_gt_u32_e32 vcc, s46, v214
	s_nop 1
	v_cndmask_b32_e32 v214, v137, v45, vcc
	v_cmp_gt_u32_e32 vcc, s46, v212
	s_nop 1
	v_cndmask_b32_e32 v47, v137, v44, vcc
	v_add_f32_e32 v44, v60, v211
	v_cmp_gt_u32_e32 vcc, s46, v210
	s_nop 1
	v_cndmask_b32_e32 v60, v137, v44, vcc
	v_cmp_gt_u32_e32 vcc, s46, v208
	s_nop 1
	v_cndmask_b32_e32 v45, v137, v43, vcc
	v_add_f32_e32 v43, v59, v207
	v_cmp_gt_u32_e32 vcc, s46, v206
	s_nop 1
	v_cndmask_b32_e32 v206, v137, v43, vcc
	v_cmp_gt_u32_e32 vcc, s46, v204
	s_nop 1
	v_cndmask_b32_e32 v43, v137, v42, vcc
	v_add_f32_e32 v42, v58, v203
	v_cmp_gt_u32_e32 vcc, s46, v202
	s_nop 1
	v_cndmask_b32_e32 v58, v137, v42, vcc
	v_cmp_gt_u32_e32 vcc, s46, v200
	s_nop 1
	v_cndmask_b32_e32 v46, v137, v41, vcc
	v_add_f32_e32 v41, v57, v199
	v_cmp_gt_u32_e32 vcc, s46, v198
	s_nop 1
	v_cndmask_b32_e32 v198, v137, v41, vcc
	v_cmp_gt_u32_e32 vcc, s46, v196
	s_nop 1
	v_cndmask_b32_e32 v44, v137, v40, vcc
	v_add_f32_e32 v40, v56, v195
	v_cmp_gt_u32_e32 vcc, s46, v194
	s_nop 1
	v_cndmask_b32_e32 v56, v137, v40, vcc
	v_cmp_gt_u32_e32 vcc, s46, v192
	s_nop 1
	v_cndmask_b32_e32 v42, v137, v39, vcc
	v_add_f32_e32 v39, v55, v191
	v_cmp_gt_u32_e32 vcc, s46, v190
	s_nop 1
	v_cndmask_b32_e32 v55, v137, v39, vcc
	v_cmp_gt_u32_e32 vcc, s46, v188
	s_nop 1
	v_cndmask_b32_e32 v41, v137, v38, vcc
	v_add_f32_e32 v38, v54, v185
	v_cmp_gt_u32_e32 vcc, s46, v184
	s_nop 1
	v_cndmask_b32_e32 v61, v137, v38, vcc
	v_cmp_gt_u32_e32 vcc, s46, v182
	v_add_f32_e32 v38, v53, v181
	s_nop 0
	v_cndmask_b32_e32 v37, v137, v37, vcc
	v_cmp_gt_u32_e32 vcc, s46, v180
	s_nop 1
	v_cndmask_b32_e32 v40, v137, v38, vcc
	v_cmp_gt_u32_e32 vcc, s46, v178
	v_add_f32_e32 v38, v52, v177
	s_nop 0
	v_cndmask_b32_e32 v36, v137, v36, vcc
	v_cmp_gt_u32_e32 vcc, s46, v176
	s_nop 1
	v_cndmask_b32_e32 v39, v137, v38, vcc
	v_cmp_gt_u32_e32 vcc, s46, v174
	s_nop 1
	v_cndmask_b32_e32 v38, v137, v35, vcc
	v_add_f32_e32 v35, v51, v173
	v_cmp_gt_u32_e32 vcc, s46, v172
	s_nop 1
	v_cndmask_b32_e32 v52, v137, v35, vcc
	v_cmp_gt_u32_e32 vcc, s46, v170
	s_nop 1
	v_cndmask_b32_e32 v35, v137, v34, vcc
	v_add_f32_e32 v34, v50, v169
	v_cmp_gt_u32_e32 vcc, s46, v168
	s_nop 1
	v_cndmask_b32_e32 v50, v137, v34, vcc
	v_max3_f32 v34, v137, v50, v35
	v_cmp_gt_u32_e32 vcc, s46, v186
	v_max3_f32 v34, v34, v52, v38
	v_max3_f32 v34, v34, v39, v36
	v_max3_f32 v34, v34, v40, v37
	v_cndmask_b32_e32 v0, v137, v0, vcc
	v_max3_f32 v34, v34, v61, v41
	v_max3_f32 v34, v34, v55, v42
	v_max3_f32 v34, v34, v56, v44
	v_max3_f32 v34, v34, v198, v46
	v_max3_f32 v34, v34, v58, v43
	v_max3_f32 v34, v34, v206, v45
	v_max3_f32 v34, v34, v60, v47
	v_max3_f32 v34, v34, v214, v48
	v_max3_f32 v34, v34, v62, v220
	v_max3_f32 v34, v34, v64, v224
	v_max3_f32 v34, v34, v226, v228
	v_max3_f32 v34, v34, v187, v0
	ds_bpermute_b32 v49, v161, v34
	v_max_f32_e32 v34, v34, v34
	s_waitcnt lgkmcnt(0)
	v_max_f32_e32 v49, v49, v49
	v_max_f32_e32 v171, v34, v49
	v_max_f32_e32 v34, v166, v166
	v_max_f32_e32 v34, v34, v171
	v_sub_f32_e32 v49, v50, v34
	v_sub_f32_e32 v35, v35, v34
	v_exp_f32_e32 v51, v49
	v_exp_f32_e32 v35, v35
	v_sub_f32_e32 v49, v52, v34
	v_sub_f32_e32 v38, v38, v34
	v_exp_f32_e32 v54, v49
	v_exp_f32_e32 v38, v38
	v_sub_f32_e32 v39, v39, v34
	v_sub_f32_e32 v36, v36, v34
	v_add_f32_e32 v49, v51, v35
	v_exp_f32_e32 v57, v39
	v_exp_f32_e32 v39, v36
	v_sub_f32_e32 v36, v40, v34
	v_add_f32_e32 v49, 0, v49
	v_add_f32_e32 v50, v54, v38
	v_exp_f32_e32 v59, v36
	v_sub_f32_e32 v36, v37, v34
	v_exp_f32_e32 v40, v36
	v_add_f32_e32 v36, v50, v49
	v_sub_f32_e32 v49, v61, v34
	v_exp_f32_e32 v61, v49
	v_sub_f32_e32 v41, v41, v34
	v_sub_f32_e32 v49, v55, v34
	v_exp_f32_e32 v41, v41
	v_exp_f32_e32 v63, v49
	v_sub_f32_e32 v42, v42, v34
	v_sub_f32_e32 v49, v56, v34
	v_exp_f32_e32 v42, v42
	v_exp_f32_e32 v65, v49
	v_sub_f32_e32 v44, v44, v34
	v_sub_f32_e32 v49, v198, v34
	v_add_f32_e32 v37, v57, v39
	v_exp_f32_e32 v44, v44
	v_exp_f32_e32 v169, v49
	v_sub_f32_e32 v46, v46, v34
	v_sub_f32_e32 v49, v58, v34
	v_add_f32_e32 v36, v37, v36
	v_add_f32_e32 v37, v59, v40
	v_exp_f32_e32 v46, v46
	v_exp_f32_e32 v52, v49
	v_sub_f32_e32 v43, v43, v34
	v_sub_f32_e32 v49, v206, v34
	v_add_f32_e32 v36, v37, v36
	v_add_f32_e32 v37, v61, v41
	v_exp_f32_e32 v43, v43
	v_exp_f32_e32 v55, v49
	v_sub_f32_e32 v45, v45, v34
	v_sub_f32_e32 v49, v60, v34
	v_add_f32_e32 v36, v37, v36
	v_add_f32_e32 v37, v63, v42
	v_exp_f32_e32 v45, v45
	v_exp_f32_e32 v58, v49
	v_sub_f32_e32 v47, v47, v34
	v_sub_f32_e32 v49, v214, v34
	v_add_f32_e32 v36, v37, v36
	v_add_f32_e32 v37, v65, v44
	v_exp_f32_e32 v47, v47
	v_exp_f32_e32 v60, v49
	v_sub_f32_e32 v48, v48, v34
	v_sub_f32_e32 v49, v62, v34
	v_add_f32_e32 v36, v37, v36
	v_add_f32_e32 v37, v169, v46
	v_exp_f32_e32 v48, v48
	v_exp_f32_e32 v62, v49
	v_sub_f32_e32 v49, v220, v34
	v_sub_f32_e32 v50, v64, v34
	v_add_f32_e32 v36, v37, v36
	v_add_f32_e32 v37, v52, v43
	v_exp_f32_e32 v49, v49
	v_exp_f32_e32 v64, v50
	v_sub_f32_e32 v50, v224, v34
	v_sub_f32_e32 v53, v226, v34
	v_add_f32_e32 v36, v37, v36
	v_add_f32_e32 v37, v55, v45
	v_exp_f32_e32 v50, v50
	v_exp_f32_e32 v168, v53
	v_sub_f32_e32 v53, v228, v34
	v_add_f32_e32 v36, v37, v36
	v_add_f32_e32 v37, v58, v47
	v_exp_f32_e32 v53, v53
	v_sub_f32_e32 v56, v187, v34
	v_sub_f32_e32 v0, v0, v34
	v_add_f32_e32 v36, v37, v36
	v_add_f32_e32 v37, v60, v48
	v_exp_f32_e32 v170, v56
	v_exp_f32_e32 v56, v0
	v_add_f32_e32 v36, v37, v36
	v_add_f32_e32 v37, v62, v49
	v_add_f32_e32 v36, v37, v36
	v_add_f32_e32 v37, v64, v50
	v_add_f32_e32 v0, v37, v36
	v_add_f32_e32 v36, v168, v53
	v_add_f32_e32 v0, v36, v0
	v_add_f32_e32 v36, v170, v56
	v_add_f32_e32 v36, v36, v0
	v_sub_f32_e32 v172, v166, v34
	ds_bpermute_b32 v37, v161, v36
	v_exp_f32_e32 v0, v172
	v_cmp_gt_f32_e32 vcc, v171, v166
	s_cbranch_vccz .LBB0_1147
	v_pk_mul_f32 v[32:33], v[32:33], v[0:1] op_sel_hi:[1,0]
	v_pk_mul_f32 v[30:31], v[30:31], v[0:1] op_sel_hi:[1,0]
	v_pk_mul_f32 v[28:29], v[28:29], v[0:1] op_sel_hi:[1,0]
	v_pk_mul_f32 v[26:27], v[26:27], v[0:1] op_sel_hi:[1,0]
	v_pk_mul_f32 v[24:25], v[24:25], v[0:1] op_sel_hi:[1,0]
	v_pk_mul_f32 v[22:23], v[22:23], v[0:1] op_sel_hi:[1,0]
	v_pk_mul_f32 v[20:21], v[20:21], v[0:1] op_sel_hi:[1,0]
	v_pk_mul_f32 v[18:19], v[18:19], v[0:1] op_sel_hi:[1,0]
	v_pk_mul_f32 v[16:17], v[16:17], v[0:1] op_sel_hi:[1,0]
	v_pk_mul_f32 v[14:15], v[14:15], v[0:1] op_sel_hi:[1,0]
	v_pk_mul_f32 v[12:13], v[12:13], v[0:1] op_sel_hi:[1,0]
	v_pk_mul_f32 v[10:11], v[10:11], v[0:1] op_sel_hi:[1,0]
	v_pk_mul_f32 v[8:9], v[8:9], v[0:1] op_sel_hi:[1,0]
	v_pk_mul_f32 v[6:7], v[6:7], v[0:1] op_sel_hi:[1,0]
	v_pk_mul_f32 v[4:5], v[4:5], v[0:1] op_sel_hi:[1,0]
	v_pk_mul_f32 v[2:3], v[2:3], v[0:1] op_sel_hi:[1,0]

.LBB0_1149:
	v_add_f32_e32 v35, v36, v37
	v_fmac_f32_e32 v35, v165, v0
	s_andn2_b64 vcc, exec, s[16:17]
	s_waitcnt lgkmcnt(0)
	s_barrier
	s_cbranch_vccz .LBB0_1098
	v_mov_b32_e32 v166, v34
	v_mov_b32_e32 v165, v35
	s_mov_b32 s8, s69
	s_mov_b32 s9, s12
	s_branch .LBB0_1109

.LBB0_1502:
	v_max3_f32 v34, v191, v66, v82
	s_nop 8
	v_max_f32_e32 v36, v177, v177
	v_max3_f32 v34, v34, v67, v83
	v_max3_f32 v34, v34, v68, v84
	v_max3_f32 v34, v34, v69, v85
	v_max3_f32 v34, v34, v70, v86
	v_max3_f32 v34, v34, v71, v87
	v_max3_f32 v34, v34, v72, v88
	v_max3_f32 v34, v34, v73, v89
	v_max3_f32 v34, v34, v74, v90
	v_max3_f32 v34, v34, v75, v91
	v_max3_f32 v34, v34, v76, v92
	v_max3_f32 v34, v34, v77, v93
	v_max3_f32 v34, v34, v78, v94
	v_max3_f32 v34, v34, v79, v95
	v_max3_f32 v34, v34, v80, v96
	v_max3_f32 v34, v34, v81, v97
	ds_bpermute_b32 v35, v197, v34
	v_max_f32_e32 v34, v34, v34
	s_waitcnt lgkmcnt(0)
	v_max_f32_e32 v35, v35, v35
	v_max_f32_e32 v174, v34, v35
	v_max_f32_e32 v35, v36, v174
	v_sub_f32_e32 v34, v66, v35
	v_sub_f32_e32 v36, v82, v35
	v_exp_f32_e32 v53, v34
	v_sub_f32_e32 v34, v67, v35
	v_exp_f32_e32 v36, v36
	v_exp_f32_e32 v55, v34
	v_sub_f32_e32 v34, v83, v35
	v_sub_f32_e32 v40, v68, v35
	v_exp_f32_e32 v39, v34
	v_exp_f32_e32 v58, v40
	v_sub_f32_e32 v40, v84, v35
	v_sub_f32_e32 v41, v69, v35
	v_exp_f32_e32 v40, v40
	v_exp_f32_e32 v60, v41
	v_sub_f32_e32 v41, v85, v35
	v_sub_f32_e32 v42, v70, v35
	v_sub_f32_e32 v44, v72, v35
	v_exp_f32_e32 v41, v41
	v_exp_f32_e32 v62, v42
	v_sub_f32_e32 v42, v86, v35
	v_sub_f32_e32 v43, v71, v35
	v_exp_f32_e32 v66, v44
	v_sub_f32_e32 v44, v88, v35
	v_add_f32_e32 v37, v53, v36
	v_exp_f32_e32 v42, v42
	v_exp_f32_e32 v64, v43
	v_sub_f32_e32 v43, v87, v35
	v_exp_f32_e32 v45, v44
	v_sub_f32_e32 v44, v73, v35
	v_add_f32_e32 v37, 0, v37
	v_add_f32_e32 v38, v55, v39
	v_exp_f32_e32 v43, v43
	v_exp_f32_e32 v68, v44
	v_sub_f32_e32 v44, v89, v35
	v_add_f32_e32 v37, v38, v37
	v_add_f32_e32 v38, v58, v40
	v_exp_f32_e32 v47, v44
	v_sub_f32_e32 v44, v74, v35
	v_add_f32_e32 v37, v38, v37
	v_add_f32_e32 v38, v60, v41
	v_exp_f32_e32 v52, v44
	v_sub_f32_e32 v44, v90, v35
	v_sub_f32_e32 v46, v75, v35
	v_add_f32_e32 v37, v38, v37
	v_add_f32_e32 v38, v62, v42
	v_exp_f32_e32 v44, v44
	v_exp_f32_e32 v56, v46
	v_sub_f32_e32 v46, v91, v35
	v_sub_f32_e32 v48, v76, v35
	v_add_f32_e32 v37, v38, v37
	v_add_f32_e32 v38, v64, v43
	v_exp_f32_e32 v46, v46
	v_exp_f32_e32 v59, v48
	v_sub_f32_e32 v48, v92, v35
	v_sub_f32_e32 v49, v77, v35
	v_add_f32_e32 v37, v38, v37
	v_add_f32_e32 v38, v66, v45
	v_exp_f32_e32 v48, v48
	v_exp_f32_e32 v61, v49
	v_sub_f32_e32 v49, v93, v35
	v_sub_f32_e32 v50, v78, v35
	v_add_f32_e32 v37, v38, v37
	v_add_f32_e32 v38, v68, v47
	v_exp_f32_e32 v49, v49
	v_exp_f32_e32 v63, v50
	v_sub_f32_e32 v50, v94, v35
	v_sub_f32_e32 v51, v79, v35
	v_add_f32_e32 v37, v38, v37
	v_add_f32_e32 v38, v52, v44
	v_exp_f32_e32 v50, v50
	v_exp_f32_e32 v65, v51
	v_sub_f32_e32 v51, v95, v35
	v_sub_f32_e32 v54, v80, v35
	v_add_f32_e32 v37, v38, v37
	v_add_f32_e32 v38, v56, v46
	v_exp_f32_e32 v51, v51
	v_exp_f32_e32 v67, v54
	v_sub_f32_e32 v54, v96, v35
	v_sub_f32_e32 v57, v81, v35
	v_add_f32_e32 v37, v38, v37
	v_add_f32_e32 v38, v59, v48
	v_exp_f32_e32 v54, v54
	v_exp_f32_e32 v69, v57
	v_sub_f32_e32 v57, v97, v35
	v_add_f32_e32 v37, v38, v37
	v_add_f32_e32 v38, v61, v49
	v_exp_f32_e32 v57, v57
	v_add_f32_e32 v37, v38, v37
	v_add_f32_e32 v38, v63, v50
	v_add_f32_e32 v37, v38, v37
	v_add_f32_e32 v38, v65, v51
	v_add_f32_e32 v37, v38, v37
	v_add_f32_e32 v38, v67, v54
	v_add_f32_e32 v37, v38, v37
	v_add_f32_e32 v38, v69, v57
	v_add_f32_e32 v37, v38, v37
	v_sub_f32_e32 v34, v177, v35
	ds_bpermute_b32 v38, v197, v37
	v_exp_f32_e32 v34, v34
	v_cmp_gt_f32_e32 vcc, v174, v177
	s_cbranch_vccz .LBB0_1504
	v_pk_mul_f32 v[16:17], v[16:17], v[34:35] op_sel_hi:[1,0]
	v_pk_mul_f32 v[14:15], v[14:15], v[34:35] op_sel_hi:[1,0]
	v_pk_mul_f32 v[12:13], v[12:13], v[34:35] op_sel_hi:[1,0]
	v_pk_mul_f32 v[10:11], v[10:11], v[34:35] op_sel_hi:[1,0]
	v_pk_mul_f32 v[8:9], v[8:9], v[34:35] op_sel_hi:[1,0]
	v_pk_mul_f32 v[6:7], v[6:7], v[34:35] op_sel_hi:[1,0]
	v_pk_mul_f32 v[4:5], v[4:5], v[34:35] op_sel_hi:[1,0]
	v_pk_mul_f32 v[2:3], v[2:3], v[34:35] op_sel_hi:[1,0]
	v_pk_mul_f32 v[32:33], v[32:33], v[34:35] op_sel_hi:[1,0]
	v_pk_mul_f32 v[30:31], v[30:31], v[34:35] op_sel_hi:[1,0]
	v_pk_mul_f32 v[28:29], v[28:29], v[34:35] op_sel_hi:[1,0]
	v_pk_mul_f32 v[26:27], v[26:27], v[34:35] op_sel_hi:[1,0]
	v_pk_mul_f32 v[24:25], v[24:25], v[34:35] op_sel_hi:[1,0]
	v_pk_mul_f32 v[22:23], v[22:23], v[34:35] op_sel_hi:[1,0]
	v_pk_mul_f32 v[20:21], v[20:21], v[34:35] op_sel_hi:[1,0]
	v_pk_mul_f32 v[18:19], v[18:19], v[34:35] op_sel_hi:[1,0]

.LBB0_1506:
	v_add_f32_e32 v52, v37, v38
	v_fmac_f32_e32 v52, v176, v34
	s_andn2_b64 vcc, exec, s[12:13]
	s_waitcnt lgkmcnt(0)
	s_barrier
	s_cbranch_vccz .LBB0_1539
	v_mov_b32_e32 v177, v35
	v_mov_b32_e32 v176, v52
	s_mov_b32 s8, s74
	s_mov_b32 s9, s66
	s_branch .LBB0_1460

.LBB0_1581:
	v_max3_f32 v0, v191, v66, v82
	s_nop 8
	v_max_f32_e32 v35, v148, v148
	v_max3_f32 v0, v0, v67, v83
	v_max3_f32 v0, v0, v68, v84
	v_max3_f32 v0, v0, v69, v85
	v_max3_f32 v0, v0, v70, v86
	v_max3_f32 v0, v0, v71, v87
	v_max3_f32 v0, v0, v72, v88
	v_max3_f32 v0, v0, v73, v89
	v_max3_f32 v0, v0, v74, v90
	v_max3_f32 v0, v0, v75, v91
	v_max3_f32 v0, v0, v76, v92
	v_max3_f32 v0, v0, v77, v93
	v_max3_f32 v0, v0, v78, v94
	v_max3_f32 v0, v0, v79, v95
	v_max3_f32 v0, v0, v80, v96
	v_max3_f32 v0, v0, v81, v97
	ds_bpermute_b32 v34, v197, v0
	v_max_f32_e32 v0, v0, v0
	s_waitcnt lgkmcnt(0)
	v_max_f32_e32 v34, v34, v34
	v_max_f32_e32 v221, v0, v34
	v_max_f32_e32 v34, v35, v221
	v_sub_f32_e32 v0, v66, v34
	v_sub_f32_e32 v35, v82, v34
	v_exp_f32_e32 v52, v0
	v_sub_f32_e32 v0, v67, v34
	v_exp_f32_e32 v35, v35
	v_exp_f32_e32 v54, v0
	v_sub_f32_e32 v0, v83, v34
	v_sub_f32_e32 v39, v68, v34
	v_exp_f32_e32 v38, v0
	v_exp_f32_e32 v57, v39
	v_sub_f32_e32 v39, v84, v34
	v_sub_f32_e32 v40, v69, v34
	v_exp_f32_e32 v39, v39
	v_exp_f32_e32 v59, v40
	v_sub_f32_e32 v40, v85, v34
	v_sub_f32_e32 v41, v70, v34
	v_sub_f32_e32 v43, v72, v34
	v_exp_f32_e32 v40, v40
	v_exp_f32_e32 v61, v41
	v_sub_f32_e32 v41, v86, v34
	v_sub_f32_e32 v42, v71, v34
	v_exp_f32_e32 v65, v43
	v_sub_f32_e32 v43, v88, v34
	v_add_f32_e32 v36, v52, v35
	v_exp_f32_e32 v41, v41
	v_exp_f32_e32 v63, v42
	v_sub_f32_e32 v42, v87, v34
	v_exp_f32_e32 v44, v43
	v_sub_f32_e32 v43, v73, v34
	v_add_f32_e32 v36, 0, v36
	v_add_f32_e32 v37, v54, v38
	v_exp_f32_e32 v42, v42
	v_exp_f32_e32 v67, v43
	v_sub_f32_e32 v43, v89, v34
	v_add_f32_e32 v36, v37, v36
	v_add_f32_e32 v37, v57, v39
	v_exp_f32_e32 v46, v43
	v_sub_f32_e32 v43, v74, v34
	v_add_f32_e32 v36, v37, v36
	v_add_f32_e32 v37, v59, v40
	v_exp_f32_e32 v51, v43
	v_sub_f32_e32 v43, v90, v34
	v_sub_f32_e32 v45, v75, v34
	v_add_f32_e32 v36, v37, v36
	v_add_f32_e32 v37, v61, v41
	v_exp_f32_e32 v43, v43
	v_exp_f32_e32 v55, v45
	v_sub_f32_e32 v45, v91, v34
	v_sub_f32_e32 v47, v76, v34
	v_add_f32_e32 v36, v37, v36
	v_add_f32_e32 v37, v63, v42
	v_exp_f32_e32 v45, v45
	v_exp_f32_e32 v58, v47
	v_sub_f32_e32 v47, v92, v34
	v_sub_f32_e32 v48, v77, v34
	v_add_f32_e32 v36, v37, v36
	v_add_f32_e32 v37, v65, v44
	v_exp_f32_e32 v47, v47
	v_exp_f32_e32 v60, v48
	v_sub_f32_e32 v48, v93, v34
	v_sub_f32_e32 v49, v78, v34
	v_add_f32_e32 v36, v37, v36
	v_add_f32_e32 v37, v67, v46
	v_exp_f32_e32 v48, v48
	v_exp_f32_e32 v62, v49
	v_sub_f32_e32 v49, v94, v34
	v_sub_f32_e32 v50, v79, v34
	v_add_f32_e32 v36, v37, v36
	v_add_f32_e32 v37, v51, v43
	v_exp_f32_e32 v49, v49
	v_exp_f32_e32 v64, v50
	v_sub_f32_e32 v50, v95, v34
	v_sub_f32_e32 v53, v80, v34
	v_add_f32_e32 v36, v37, v36
	v_add_f32_e32 v37, v55, v45
	v_exp_f32_e32 v50, v50
	v_exp_f32_e32 v66, v53
	v_sub_f32_e32 v53, v96, v34
	v_sub_f32_e32 v56, v81, v34
	v_add_f32_e32 v36, v37, v36
	v_add_f32_e32 v37, v58, v47
	v_exp_f32_e32 v53, v53
	v_exp_f32_e32 v68, v56
	v_sub_f32_e32 v56, v97, v34
	v_add_f32_e32 v36, v37, v36
	v_add_f32_e32 v37, v60, v48
	v_exp_f32_e32 v56, v56
	v_add_f32_e32 v36, v37, v36
	v_add_f32_e32 v37, v62, v49
	v_add_f32_e32 v36, v37, v36
	v_add_f32_e32 v37, v64, v50
	v_add_f32_e32 v36, v37, v36
	v_add_f32_e32 v37, v66, v53
	v_add_f32_e32 v36, v37, v36
	v_add_f32_e32 v37, v68, v56
	v_add_f32_e32 v36, v37, v36
	v_sub_f32_e32 v0, v148, v34
	ds_bpermute_b32 v37, v197, v36
	v_exp_f32_e32 v0, v0
	v_cmp_gt_f32_e32 vcc, v221, v148
	s_cbranch_vccz .LBB0_1583
	v_pk_mul_f32 v[32:33], v[32:33], v[0:1] op_sel_hi:[1,0]
	v_pk_mul_f32 v[30:31], v[30:31], v[0:1] op_sel_hi:[1,0]
	v_pk_mul_f32 v[28:29], v[28:29], v[0:1] op_sel_hi:[1,0]
	v_pk_mul_f32 v[26:27], v[26:27], v[0:1] op_sel_hi:[1,0]
	v_pk_mul_f32 v[24:25], v[24:25], v[0:1] op_sel_hi:[1,0]
	v_pk_mul_f32 v[22:23], v[22:23], v[0:1] op_sel_hi:[1,0]
	v_pk_mul_f32 v[20:21], v[20:21], v[0:1] op_sel_hi:[1,0]
	v_pk_mul_f32 v[18:19], v[18:19], v[0:1] op_sel_hi:[1,0]
	v_pk_mul_f32 v[16:17], v[16:17], v[0:1] op_sel_hi:[1,0]
	v_pk_mul_f32 v[14:15], v[14:15], v[0:1] op_sel_hi:[1,0]
	v_pk_mul_f32 v[12:13], v[12:13], v[0:1] op_sel_hi:[1,0]
	v_pk_mul_f32 v[10:11], v[10:11], v[0:1] op_sel_hi:[1,0]
	v_pk_mul_f32 v[8:9], v[8:9], v[0:1] op_sel_hi:[1,0]
	v_pk_mul_f32 v[6:7], v[6:7], v[0:1] op_sel_hi:[1,0]
	v_pk_mul_f32 v[4:5], v[4:5], v[0:1] op_sel_hi:[1,0]
	v_pk_mul_f32 v[2:3], v[2:3], v[0:1] op_sel_hi:[1,0]

.LBB0_1585:
	v_add_f32_e32 v54, v36, v37
	v_fmac_f32_e32 v54, v146, v0
	s_andn2_b64 vcc, exec, s[10:11]
	s_waitcnt lgkmcnt(0)
	s_barrier
	s_cbranch_vccz .LBB0_1617
	v_mov_b32_e32 v148, v34
	v_mov_b32_e32 v146, v54
	s_mov_b32 s8, s18
	s_mov_b32 s9, s19
	s_branch .LBB0_1541
